# GU: per-phase K/C LDS tables + next tile's first 12 fragment ds_reads hoisted to the top of the tile prologue (ahead of the base-pointer SALU)
# speedup vs baseline: 1.0032x; 1.0021x over previous
.LBB0_791:
	s_add_i32 s76, 0, 0x10000
	v_add_u32_e32 v138, s76, v142
	ds_read_b128 v[146:149], v138
	ds_read_b128 v[150:153], v138 offset:1024
	ds_read_b128 v[166:169], v138 offset:2048
	ds_read_b128 v[170:173], v138 offset:3072
	ds_read_b128 v[174:177], v145
	ds_read_b128 v[178:181], v145 offset:1024
	ds_read_b128 v[182:185], v145 offset:2048
	ds_read_b128 v[186:189], v145 offset:3072
	ds_read_b128 v[214:217], v145 offset:4096
	ds_read_b128 v[218:221], v145 offset:5120
	ds_read_b128 v[222:225], v145 offset:6144
	ds_read_b128 v[226:229], v145 offset:7168
	v_mov_b64_e32 v[0:1], 0x580
	s_ashr_i32 s21, s20, 31
	v_cmp_lt_i64_e32 vcc, s[22:23], v[0:1]
	s_lshl_b64 s[22:23], s[20:21], 19
	s_add_u32 s22, s96, s22
	s_addc_u32 s23, s97, s23
	s_and_b64 s[24:25], vcc, exec
	s_cselect_b32 s9, s23, s59
	s_cselect_b32 s21, s22, s58
	s_ashr_i32 s19, s18, 31
	s_lshl_b64 s[24:25], s[18:19], 19
	s_add_u32 s24, s35, s24
	s_addc_u32 s25, s47, s25
	s_and_b64 s[66:67], vcc, exec
	s_cselect_b32 s19, s25, s63
	s_cselect_b32 s29, s24, s62
	s_add_u32 s58, s58, 0x40080
	s_addc_u32 s59, s59, 0
	s_add_u32 s43, s62, 0x100
	s_addc_u32 s51, s63, 0
	s_mov_b32 s75, -2
	s_add_u32 s62, s58, 0xfffc0080
	s_addc_u32 s63, s59, -1
	s_cmp_eq_u32 s75, 12
	s_cselect_b32 s67, s9, s63
	s_cselect_b32 s66, s21, s62
	s_cselect_b32 s63, s19, s51
	s_cselect_b32 s62, s29, s43
	s_add_i32 m0, s48, 0xc000
	global_load_lds_dwordx4 v134, s[58:59]
	s_add_i32 m0, s48, 0xe000
	s_nop 0
	global_load_lds_dwordx4 v136, s[58:59]
	s_waitcnt lgkmcnt(8)
	s_barrier
	s_waitcnt lgkmcnt(0)
	s_setprio 1
	s_waitcnt lgkmcnt(0)
	v_mfma_f32_16x16x32_bf16 v[124:127], v[146:149], v[174:177], 0
	v_mfma_f32_16x16x32_bf16 v[116:119], v[166:169], v[174:177], 0
	v_mfma_f32_16x16x32_bf16 v[108:111], v[146:149], v[182:185], 0
	v_mfma_f32_16x16x32_bf16 v[100:103], v[166:169], v[182:185], 0
	v_mfma_f32_16x16x32_bf16 v[92:95], v[146:149], v[214:217], 0
	v_mfma_f32_16x16x32_bf16 v[84:87], v[166:169], v[214:217], 0
	v_mfma_f32_16x16x32_bf16 v[76:79], v[146:149], v[222:225], 0
	v_mfma_f32_16x16x32_bf16 v[68:71], v[166:169], v[222:225], 0
	v_mfma_f32_16x16x32_bf16 v[124:127], v[150:153], v[178:181], v[124:127]
	v_mfma_f32_16x16x32_bf16 v[116:119], v[170:173], v[178:181], v[116:119]
	v_mfma_f32_16x16x32_bf16 v[108:111], v[150:153], v[186:189], v[108:111]
	v_mfma_f32_16x16x32_bf16 v[100:103], v[170:173], v[186:189], v[100:103]
	v_mfma_f32_16x16x32_bf16 v[92:95], v[150:153], v[218:221], v[92:95]
	v_mfma_f32_16x16x32_bf16 v[84:87], v[170:173], v[218:221], v[84:87]
	v_mfma_f32_16x16x32_bf16 v[76:79], v[150:153], v[226:229], v[76:79]
	v_mfma_f32_16x16x32_bf16 v[68:71], v[170:173], v[226:229], v[68:71]
	s_setprio 0
	s_barrier
	s_add_i32 s78, 0, 0x14000
	v_add_u32_e32 v138, s78, v142
	s_add_i32 s76, s76, s31
	ds_read_b128 v[230:233], v138
	ds_read_b128 v[234:237], v138 offset:1024
	ds_read_b128 v[238:241], v138 offset:2048
	ds_read_b128 v[242:245], v138 offset:3072
	v_lshl_add_u64 v[138:139], s[62:63], 0, v[158:159]
	s_mov_b32 m0, s76
	v_lshl_add_u64 v[154:155], s[62:63], 0, v[132:133]
	global_load_lds_dwordx4 v158, s[62:63]
	s_add_i32 m0, s76, 0x2000
	s_nop 0
	global_load_lds_dwordx4 v132, s[62:63]
	s_barrier
	s_waitcnt lgkmcnt(0)
	s_setprio 1
	s_waitcnt lgkmcnt(0)
	v_mfma_f32_16x16x32_bf16 v[120:123], v[230:233], v[174:177], 0
	v_mfma_f32_16x16x32_bf16 v[112:115], v[238:241], v[174:177], 0
	v_mfma_f32_16x16x32_bf16 v[104:107], v[230:233], v[182:185], 0
	v_mfma_f32_16x16x32_bf16 v[96:99], v[238:241], v[182:185], 0
	v_mfma_f32_16x16x32_bf16 v[88:91], v[230:233], v[214:217], 0
	v_mfma_f32_16x16x32_bf16 v[80:83], v[238:241], v[214:217], 0
	v_mfma_f32_16x16x32_bf16 v[72:75], v[230:233], v[222:225], 0
	v_mfma_f32_16x16x32_bf16 v[64:67], v[238:241], v[222:225], 0
	v_mfma_f32_16x16x32_bf16 v[120:123], v[234:237], v[178:181], v[120:123]
	v_mfma_f32_16x16x32_bf16 v[112:115], v[242:245], v[178:181], v[112:115]
	v_mfma_f32_16x16x32_bf16 v[104:107], v[234:237], v[186:189], v[104:107]
	v_mfma_f32_16x16x32_bf16 v[96:99], v[242:245], v[186:189], v[96:99]
	v_mfma_f32_16x16x32_bf16 v[88:91], v[234:237], v[218:221], v[88:91]
	v_mfma_f32_16x16x32_bf16 v[80:83], v[242:245], v[218:221], v[80:83]
	v_mfma_f32_16x16x32_bf16 v[72:75], v[234:237], v[226:229], v[72:75]
	v_mfma_f32_16x16x32_bf16 v[64:67], v[242:245], v[226:229], v[64:67]
	s_setprio 0
	s_mov_b32 m0, s48
	v_lshl_add_u64 v[190:191], s[66:67], 0, v[128:129]
	s_barrier
	ds_read_b128 v[174:177], v145 offset:16384
	ds_read_b128 v[178:181], v145 offset:17408
	ds_read_b128 v[182:185], v145 offset:18432
	ds_read_b128 v[186:189], v145 offset:19456
	ds_read_b128 v[214:217], v145 offset:20480
	ds_read_b128 v[218:221], v145 offset:21504
	ds_read_b128 v[222:225], v145 offset:22528
	ds_read_b128 v[226:229], v145 offset:23552
	global_load_lds_dwordx4 v128, s[66:67]
	v_lshl_add_u64 v[202:203], s[66:67], 0, v[130:131]
	s_mov_b32 m0, s50
	s_nop 0
	global_load_lds_dwordx4 v130, s[66:67]
	s_barrier
	s_waitcnt lgkmcnt(0)
	s_setprio 1
	s_waitcnt lgkmcnt(0)
	v_mfma_f32_16x16x32_bf16 v[60:63], v[146:149], v[174:177], 0
	v_mfma_f32_16x16x32_bf16 v[52:55], v[166:169], v[174:177], 0
	v_mfma_f32_16x16x32_bf16 v[44:47], v[146:149], v[182:185], 0
	v_mfma_f32_16x16x32_bf16 v[36:39], v[166:169], v[182:185], 0
	v_mfma_f32_16x16x32_bf16 v[28:31], v[146:149], v[214:217], 0
	v_mfma_f32_16x16x32_bf16 v[20:23], v[166:169], v[214:217], 0
	v_mfma_f32_16x16x32_bf16 v[12:15], v[146:149], v[222:225], 0
	v_mfma_f32_16x16x32_bf16 v[4:7], v[166:169], v[222:225], 0
	v_mfma_f32_16x16x32_bf16 v[60:63], v[150:153], v[178:181], v[60:63]
	v_mfma_f32_16x16x32_bf16 v[52:55], v[170:173], v[178:181], v[52:55]
	v_mfma_f32_16x16x32_bf16 v[44:47], v[150:153], v[186:189], v[44:47]
	v_mfma_f32_16x16x32_bf16 v[36:39], v[170:173], v[186:189], v[36:39]
	v_mfma_f32_16x16x32_bf16 v[28:31], v[150:153], v[218:221], v[28:31]
	v_mfma_f32_16x16x32_bf16 v[20:23], v[170:173], v[218:221], v[20:23]
	v_mfma_f32_16x16x32_bf16 v[12:15], v[150:153], v[226:229], v[12:15]
	v_mfma_f32_16x16x32_bf16 v[4:7], v[170:173], v[226:229], v[4:7]
	s_setprio 0
	s_barrier
	s_add_u32 s76, s62, 0x40000
	s_addc_u32 s77, s63, 0
	s_add_i32 s78, s78, s31
	s_mov_b32 m0, s78
	s_nop 0
	global_load_lds_dwordx4 v158, s[76:77]
	s_add_i32 m0, s78, 0x2000
	s_nop 0
	global_load_lds_dwordx4 v132, s[76:77]
	s_waitcnt vmcnt(6)
	s_barrier
	s_setprio 1
	v_mfma_f32_16x16x32_bf16 v[56:59], v[230:233], v[174:177], 0
	v_mfma_f32_16x16x32_bf16 v[48:51], v[238:241], v[174:177], 0
	v_mfma_f32_16x16x32_bf16 v[40:43], v[230:233], v[182:185], 0
	v_mfma_f32_16x16x32_bf16 v[32:35], v[238:241], v[182:185], 0
	v_mfma_f32_16x16x32_bf16 v[24:27], v[230:233], v[214:217], 0
	v_mfma_f32_16x16x32_bf16 v[16:19], v[238:241], v[214:217], 0
	v_mfma_f32_16x16x32_bf16 v[8:11], v[230:233], v[222:225], 0
	v_mfma_f32_16x16x32_bf16 v[0:3], v[238:241], v[222:225], 0
	v_mfma_f32_16x16x32_bf16 v[56:59], v[234:237], v[178:181], v[56:59]
	v_mfma_f32_16x16x32_bf16 v[48:51], v[242:245], v[178:181], v[48:51]
	v_mfma_f32_16x16x32_bf16 v[40:43], v[234:237], v[186:189], v[40:43]
	v_mfma_f32_16x16x32_bf16 v[32:35], v[242:245], v[186:189], v[32:35]
	v_mfma_f32_16x16x32_bf16 v[24:27], v[234:237], v[218:221], v[24:27]
	v_mfma_f32_16x16x32_bf16 v[16:19], v[242:245], v[218:221], v[16:19]
	v_mfma_f32_16x16x32_bf16 v[8:11], v[234:237], v[226:229], v[8:11]
	v_mfma_f32_16x16x32_bf16 v[0:3], v[242:245], v[226:229], v[0:3]
	s_setprio 0
	s_add_i32 s76, 0, 0x18000
	v_add_u32_e32 v140, s76, v142
	s_barrier
	ds_read_b128 v[146:149], v140
	ds_read_b128 v[150:153], v140 offset:1024
	ds_read_b128 v[166:169], v140 offset:2048
	ds_read_b128 v[170:173], v140 offset:3072
	s_add_u32 s66, s66, 0x40000
	s_addc_u32 s67, s67, 0
	s_mov_b32 m0, s65
	ds_read_b128 v[174:177], v145 offset:32768
	ds_read_b128 v[178:181], v145 offset:33792
	ds_read_b128 v[182:185], v145 offset:34816
	ds_read_b128 v[186:189], v145 offset:35840
	ds_read_b128 v[214:217], v145 offset:36864
	ds_read_b128 v[218:221], v145 offset:37888
	ds_read_b128 v[222:225], v145 offset:38912
	ds_read_b128 v[226:229], v145 offset:39936
	global_load_lds_dwordx4 v128, s[66:67]
	s_mov_b32 m0, s68
	s_nop 0
	global_load_lds_dwordx4 v130, s[66:67]
	s_waitcnt lgkmcnt(8)
	s_barrier
	s_waitcnt lgkmcnt(0)
	s_setprio 1
	s_waitcnt lgkmcnt(0)
	v_mfma_f32_16x16x32_bf16 v[124:127], v[146:149], v[174:177], v[124:127]
	v_mfma_f32_16x16x32_bf16 v[116:119], v[166:169], v[174:177], v[116:119]
	v_mfma_f32_16x16x32_bf16 v[108:111], v[146:149], v[182:185], v[108:111]
	v_mfma_f32_16x16x32_bf16 v[100:103], v[166:169], v[182:185], v[100:103]
	v_mfma_f32_16x16x32_bf16 v[92:95], v[146:149], v[214:217], v[92:95]
	v_mfma_f32_16x16x32_bf16 v[84:87], v[166:169], v[214:217], v[84:87]
	v_mfma_f32_16x16x32_bf16 v[76:79], v[146:149], v[222:225], v[76:79]
	v_mfma_f32_16x16x32_bf16 v[68:71], v[166:169], v[222:225], v[68:71]
	v_mfma_f32_16x16x32_bf16 v[124:127], v[150:153], v[178:181], v[124:127]
	v_mfma_f32_16x16x32_bf16 v[116:119], v[170:173], v[178:181], v[116:119]
	v_mfma_f32_16x16x32_bf16 v[108:111], v[150:153], v[186:189], v[108:111]
	v_mfma_f32_16x16x32_bf16 v[100:103], v[170:173], v[186:189], v[100:103]
	v_mfma_f32_16x16x32_bf16 v[92:95], v[150:153], v[218:221], v[92:95]
	v_mfma_f32_16x16x32_bf16 v[84:87], v[170:173], v[218:221], v[84:87]
	v_mfma_f32_16x16x32_bf16 v[76:79], v[150:153], v[226:229], v[76:79]
	v_mfma_f32_16x16x32_bf16 v[68:71], v[170:173], v[226:229], v[68:71]
	s_setprio 0
	s_barrier
	s_add_i32 s66, 0, 0x1c000
	s_add_i32 s67, s76, s31
	v_add_u32_e32 v140, s66, v142
	v_lshl_add_u64 v[138:139], v[138:139], 0, s[70:71]
	s_mov_b32 m0, s67
	ds_read_b128 v[230:233], v140
	ds_read_b128 v[234:237], v140 offset:1024
	ds_read_b128 v[238:241], v140 offset:2048
	ds_read_b128 v[242:245], v140 offset:3072
	global_load_lds_dwordx4 v[138:139], off
	v_lshl_add_u64 v[138:139], v[154:155], 0, s[70:71]
	s_add_i32 m0, s67, 0x2000
	s_nop 0
	global_load_lds_dwordx4 v[138:139], off
	s_barrier
	s_waitcnt lgkmcnt(0)
	s_setprio 1
	s_waitcnt lgkmcnt(0)
	v_mfma_f32_16x16x32_bf16 v[120:123], v[230:233], v[174:177], v[120:123]
	v_mfma_f32_16x16x32_bf16 v[112:115], v[238:241], v[174:177], v[112:115]
	v_mfma_f32_16x16x32_bf16 v[104:107], v[230:233], v[182:185], v[104:107]
	v_mfma_f32_16x16x32_bf16 v[96:99], v[238:241], v[182:185], v[96:99]
	v_mfma_f32_16x16x32_bf16 v[88:91], v[230:233], v[214:217], v[88:91]
	v_mfma_f32_16x16x32_bf16 v[80:83], v[238:241], v[214:217], v[80:83]
	v_mfma_f32_16x16x32_bf16 v[72:75], v[230:233], v[222:225], v[72:75]
	v_mfma_f32_16x16x32_bf16 v[64:67], v[238:241], v[222:225], v[64:67]
	v_mfma_f32_16x16x32_bf16 v[120:123], v[234:237], v[178:181], v[120:123]
	v_mfma_f32_16x16x32_bf16 v[112:115], v[242:245], v[178:181], v[112:115]
	v_mfma_f32_16x16x32_bf16 v[104:107], v[234:237], v[186:189], v[104:107]
	v_mfma_f32_16x16x32_bf16 v[96:99], v[242:245], v[186:189], v[96:99]
	v_mfma_f32_16x16x32_bf16 v[88:91], v[234:237], v[218:221], v[88:91]
	v_mfma_f32_16x16x32_bf16 v[80:83], v[242:245], v[218:221], v[80:83]
	v_mfma_f32_16x16x32_bf16 v[72:75], v[234:237], v[226:229], v[72:75]
	v_mfma_f32_16x16x32_bf16 v[64:67], v[242:245], v[226:229], v[64:67]
	s_setprio 0
	s_mov_b32 m0, s69
	v_lshl_add_u64 v[138:139], v[190:191], 0, s[70:71]
	s_barrier
	ds_read_b128 v[174:177], v145 offset:49152
	ds_read_b128 v[178:181], v145 offset:50176
	ds_read_b128 v[182:185], v145 offset:51200
	ds_read_b128 v[186:189], v145 offset:52224
	ds_read_b128 v[214:217], v145 offset:53248
	ds_read_b128 v[218:221], v145 offset:54272
	ds_read_b128 v[222:225], v145 offset:55296
	ds_read_b128 v[226:229], v145 offset:56320
	global_load_lds_dwordx4 v[138:139], off
	v_lshl_add_u64 v[138:139], v[202:203], 0, s[70:71]
	s_mov_b32 m0, s72
	s_nop 0
	global_load_lds_dwordx4 v[138:139], off
	s_barrier
	s_waitcnt lgkmcnt(0)
	s_setprio 1
	s_waitcnt lgkmcnt(0)
	v_mfma_f32_16x16x32_bf16 v[60:63], v[146:149], v[174:177], v[60:63]
	v_mfma_f32_16x16x32_bf16 v[52:55], v[166:169], v[174:177], v[52:55]
	v_mfma_f32_16x16x32_bf16 v[44:47], v[146:149], v[182:185], v[44:47]
	v_mfma_f32_16x16x32_bf16 v[36:39], v[166:169], v[182:185], v[36:39]
	v_mfma_f32_16x16x32_bf16 v[28:31], v[146:149], v[214:217], v[28:31]
	v_mfma_f32_16x16x32_bf16 v[20:23], v[166:169], v[214:217], v[20:23]
	v_mfma_f32_16x16x32_bf16 v[12:15], v[146:149], v[222:225], v[12:15]
	v_mfma_f32_16x16x32_bf16 v[4:7], v[166:169], v[222:225], v[4:7]
	v_mfma_f32_16x16x32_bf16 v[60:63], v[150:153], v[178:181], v[60:63]
	v_mfma_f32_16x16x32_bf16 v[52:55], v[170:173], v[178:181], v[52:55]
	v_mfma_f32_16x16x32_bf16 v[44:47], v[150:153], v[186:189], v[44:47]
	v_mfma_f32_16x16x32_bf16 v[36:39], v[170:173], v[186:189], v[36:39]
	v_mfma_f32_16x16x32_bf16 v[28:31], v[150:153], v[218:221], v[28:31]
	v_mfma_f32_16x16x32_bf16 v[20:23], v[170:173], v[218:221], v[20:23]
	v_mfma_f32_16x16x32_bf16 v[12:15], v[150:153], v[226:229], v[12:15]
	v_mfma_f32_16x16x32_bf16 v[4:7], v[170:173], v[226:229], v[4:7]
	s_setprio 0
	s_barrier
	s_add_u32 s62, s62, 0x40080
	s_addc_u32 s63, s63, 0
	s_add_i32 s66, s66, s31
	s_mov_b32 m0, s66
	s_nop 0
	global_load_lds_dwordx4 v158, s[62:63]
	s_add_i32 m0, s66, 0x2000
	s_nop 0
	global_load_lds_dwordx4 v132, s[62:63]
	s_waitcnt vmcnt(6)
	s_barrier
	s_setprio 1
	v_mfma_f32_16x16x32_bf16 v[56:59], v[230:233], v[174:177], v[56:59]
	v_mfma_f32_16x16x32_bf16 v[48:51], v[238:241], v[174:177], v[48:51]
	v_mfma_f32_16x16x32_bf16 v[40:43], v[230:233], v[182:185], v[40:43]
	v_mfma_f32_16x16x32_bf16 v[32:35], v[238:241], v[182:185], v[32:35]
	v_mfma_f32_16x16x32_bf16 v[24:27], v[230:233], v[214:217], v[24:27]
	v_mfma_f32_16x16x32_bf16 v[16:19], v[238:241], v[214:217], v[16:19]
	v_mfma_f32_16x16x32_bf16 v[8:11], v[230:233], v[222:225], v[8:11]
	v_mfma_f32_16x16x32_bf16 v[0:3], v[238:241], v[222:225], v[0:3]
	v_mfma_f32_16x16x32_bf16 v[56:59], v[234:237], v[178:181], v[56:59]
	v_mfma_f32_16x16x32_bf16 v[48:51], v[242:245], v[178:181], v[48:51]
	v_mfma_f32_16x16x32_bf16 v[40:43], v[234:237], v[186:189], v[40:43]
	v_mfma_f32_16x16x32_bf16 v[32:35], v[242:245], v[186:189], v[32:35]
	v_mfma_f32_16x16x32_bf16 v[24:27], v[234:237], v[218:221], v[24:27]
	v_mfma_f32_16x16x32_bf16 v[16:19], v[242:245], v[218:221], v[16:19]
	v_mfma_f32_16x16x32_bf16 v[8:11], v[234:237], v[226:229], v[8:11]
	v_mfma_f32_16x16x32_bf16 v[0:3], v[242:245], v[226:229], v[0:3]
	s_setprio 0
	s_add_i32 s75, s75, 2
	s_add_u32 s58, s58, 0x100
	s_addc_u32 s59, s59, 0
	s_add_u32 s43, s43, 0x100
	s_addc_u32 s51, s51, 0
	s_cmp_gt_u32 s75, 13
	s_barrier
	s_cbranch_scc1 .Lzp_exit3
